# speedup vs baseline: 1.0158x; 1.0020x over previous
; __device__ __forceinline__ void attn_unit(LAS unsigned char* lds, const bf16_t* Qb, const bf16_t* Kb, const bf16_t* VT, bf16_t* O1, bf16_t* OC, const float* subg, const unsigned* kmx, float lam, int b, int hm, int qb, bool first, bool has_next, int b2, int hm2) {
;     ...
;         for (int r = 0; r < 16; ++r) { sa += B0[r]; sb += B1[r]; }
;         lsum += sa + sb;
;         const u32x4 pw0 = PK4(B0, 0), pw1 = PK4(B0, 8), pw2 = PK4(B1, 0), pw3 = PK4(B1, 8);
; #pragma unroll
;         for (int db = 0; db < 4; ++db) { o[db] = MF(BF8(pw0), VLD(0, db), o[db]); o[db] = MF(BF8(pw1), VLD(1, db), o[db]); o[db] = MF(BF8(pw2), VLD(2, db), o[db]); o[db] = MF(BF8(pw3), VLD(3, db), o[db]); }
;     }
;     WAIT_BAR(0);
;     if (has_next) { const bf16_t* kb2 = Kb + (size_t)b2 * KVT * DM + hm2 * 64; const bf16_t* vb2 = VT + ((size_t)b2 * 1024 + (hm2 >> 1) * 128) * KVT;
; #pragma unroll
;         for (int j = 0; j < 4; ++j) GLDS(kb2 + (size_t)j * 64 * DM, koff, j * 8192 + kwu);
; #pragma unroll
;         for (int j = 0; j < 3; ++j) { GLDS(vb2 + j * 64, voff0, 32768 + j * 16384 + vwu); GLDS(vb2 + j * 64, voff1, 32768 + j * 16384 + vwu + 1024); } }
;     lsum += __shfl_xor(lsum, 32);
;     wsf[r32] = __builtin_amdgcn_rcpf(lsum);
;     const size_t obase = (size_t)qrow0 * DM + h * 128 + r32;
;     if ((hm & 1) == 0) {
; #pragma unroll
;         for (int q4 = 0; q4 < 4; ++q4) { const f32x4 fv = *(const LAS f32x4*)(wsf + 8 * q4 + 4 * hi);
; #pragma unroll
;             for (int s4 = 0; s4 < 4; ++s4) { const int r = 4 * q4 + s4, q = 8 * q4 + 4 * hi + s4;
; #pragma unroll
;                 for (int db = 0; db < 4; ++db) { const unsigned w = cvtpk_s(o[db][r] * fv[s4], 0.f); O1[obase + (size_t)q * DM + db * 32] = (bf16_t)(w & 0xffffu); } } }
;     } else {
;         float gs[4];
; #pragma unroll
;         for (int db = 0; db < 4; ++db) gs[db] = subg[db * 32 + r32] * (1.0f - LAMBDA_INIT);
; #pragma unroll
;         for (int q4 = 0; q4 < 4; ++q4) { const f32x4 fv = *(const LAS f32x4*)(wsf + 8 * q4 + 4 * hi);
; #pragma unroll
;             for (int s4 = 0; s4 < 4; ++s4) { const int r = 4 * q4 + s4, q = 8 * q4 + 4 * hi + s4; float ov[4]; float ss = 0.f;
; #pragma unroll
;                 for (int db = 0; db < 4; ++db) { const float x1 = __uint_as_float((unsigned)O1[obase + (size_t)q * DM + db * 32] << 16); ov[db] = x1 - lam * (o[db][r] * fv[s4]); ss += ov[db] * ov[db]; }
.LBB0_857:
	v_add_f32_e32 v80, 0, v112
	v_add_f32_e32 v81, 0, v96
	v_add_f32_e32 v80, v113, v80
	v_add_f32_e32 v81, v97, v81
	v_add_f32_e32 v80, v114, v80
	v_add_f32_e32 v81, v98, v81
	v_add_f32_e32 v80, v115, v80
	v_add_f32_e32 v81, v99, v81
	v_add_f32_e32 v80, v116, v80
	v_add_f32_e32 v81, v100, v81
	v_add_f32_e32 v80, v117, v80
	v_add_f32_e32 v81, v101, v81
	v_add_f32_e32 v80, v118, v80
	v_add_f32_e32 v81, v102, v81
	v_add_f32_e32 v80, v119, v80
	v_add_f32_e32 v81, v103, v81
	v_add_f32_e32 v80, v120, v80
	v_add_f32_e32 v81, v104, v81
	v_add_f32_e32 v80, v121, v80
	v_add_f32_e32 v81, v105, v81
	v_add_f32_e32 v80, v122, v80
	v_add_f32_e32 v81, v106, v81
	v_add_f32_e32 v80, v123, v80
	v_add_f32_e32 v81, v107, v81
	v_add_f32_e32 v80, v124, v80
	v_add_f32_e32 v81, v108, v81
	v_add_f32_e32 v80, v125, v80
	v_add_f32_e32 v81, v109, v81
	v_add_f32_e32 v80, v126, v80
	v_add_f32_e32 v81, v110, v81
	v_add_f32_e32 v80, v127, v80
	v_add_f32_e32 v81, v111, v81
	v_add_f32_e32 v80, v80, v81
	v_add_f32_e32 v80, v128, v80
	ds_bpermute_b32 v81, v205, v80
	v_ashrrev_i32_e32 v201, 31, v200
	v_lshlrev_b64 v[88:89], 10, v[200:201]
	s_mov_b64 s[2:3], -1
	s_cmp_lg_u32 s48, 0
	s_waitcnt lgkmcnt(0)
	v_add_f32_e32 v80, v80, v81
	v_rcp_f32_e32 v80, v80
	v_lshl_add_u32 v110, v214, 4, v217
	v_lshlrev_b32_e32 v198, 13, v214
	ds_write_b32 v222, v80
	v_or_b32_e32 v80, v88, v213
	v_or_b32_e32 v88, s49, v80
	s_cbranch_scc0 .LBB0_859
	v_lshlrev_b64 v[86:87], 1, v[88:89]
	v_lshl_add_u64 v[90:91], s[42:43], 0, v[86:87]
	v_mul_u32_u24_e32 v244, 0x7fe, v213
	v_mov_b32_e32 v245, 0
	v_lshl_add_u32 v244, v214, 7, v244
	v_lshl_add_u64 v[244:245], v[90:91], 0, v[244:245]
	global_load_dword v246, v[244:245], off
	v_lshl_add_u64 v[80:81], v[90:91], 0, v[198:199]
	global_load_ushort v111, v[80:81], off offset:64
	global_load_ushort v116, v[80:81], off offset:2176
	global_load_ushort v114, v[80:81], off offset:2048
	global_load_ushort v112, v[80:81], off offset:128
	global_load_ushort v113, v[80:81], off
	global_load_ushort v115, v[80:81], off offset:192
	global_load_ushort v117, v[80:81], off offset:2112
	global_load_ushort v118, v[80:81], off offset:2240
	v_lshlrev_b32_e32 v80, 2, v213
	v_or_b32_e32 v96, 0x1000, v198
	v_mov_b32_e32 v97, v199
	v_or_b32_e32 v84, 0x1800, v198
	v_mov_b32_e32 v85, v199
	global_load_dword v124, v80, s[38:39]
	global_load_dword v125, v80, s[38:39] offset:128
	global_load_dword v126, v80, s[38:39] offset:256
	global_load_dword v127, v80, s[38:39] offset:384
	v_lshl_add_u64 v[80:81], v[90:91], 0, v[96:97]
	v_lshl_add_u64 v[82:83], v[90:91], 0, v[84:85]
	global_load_ushort v128, v[80:81], off offset:64
	global_load_ushort v130, v[82:83], off offset:128
	global_load_ushort v131, v[82:83], off offset:192
	global_load_ushort v132, v[82:83], off
	global_load_ushort v129, v[80:81], off offset:128
	global_load_ushort v133, v[80:81], off
	global_load_ushort v134, v[80:81], off offset:192
	global_load_ushort v135, v[82:83], off offset:64
	ds_read_b128 v[98:101], v110
	ds_read_b128 v[80:83], v110 offset:32
	v_mov_b32_e32 v94, v16
	v_mov_b32_e32 v95, v32
	v_mov_b32_e32 v102, v48
	v_mov_b32_e32 v103, v64
	v_mov_b32_e32 v104, v17
	v_mov_b32_e32 v105, v33
	v_mov_b32_e32 v106, v49
	v_mov_b32_e32 v107, v65
	s_waitcnt lgkmcnt(1)
	v_pk_mul_f32 v[94:95], v[94:95], v[98:99] op_sel_hi:[1,0]
	v_pk_mul_f32 v[102:103], v[102:103], v[98:99] op_sel_hi:[1,0]
	v_pk_mul_f32 v[104:105], v[104:105], v[98:99] op_sel:[0,1]
	v_pk_mul_f32 v[98:99], v[106:107], v[98:99] op_sel:[0,1]
	v_mov_b32_e32 v108, v18
	v_mov_b32_e32 v109, v34
	s_mov_b32 s2, 0x358637bd
	v_mov_b64_e32 v[92:93], s[2:3]
	s_mov_b64 s[2:3], 0
	s_waitcnt vmcnt(19)
	v_lshlrev_b32_e32 v107, 16, v111
	s_waitcnt vmcnt(18)
	v_lshlrev_b32_e32 v116, 16, v116
	s_waitcnt vmcnt(17)
	v_lshlrev_b32_e32 v114, 16, v114
	s_waitcnt vmcnt(16)
	v_lshlrev_b32_e32 v112, 16, v112
	s_waitcnt vmcnt(15)
	v_lshlrev_b32_e32 v106, 16, v113
	s_waitcnt vmcnt(14)
	v_lshlrev_b32_e32 v113, 16, v115
	s_waitcnt vmcnt(13)
	v_lshlrev_b32_e32 v115, 16, v117
	s_waitcnt vmcnt(12)
	v_lshlrev_b32_e32 v117, 16, v118
	v_pk_fma_f32 v[106:107], v[196:197], v[94:95], v[106:107] neg_lo:[1,0,0] neg_hi:[1,0,0]
	v_pk_fma_f32 v[104:105], v[196:197], v[104:105], v[114:115] neg_lo:[1,0,0] neg_hi:[1,0,0]
	v_pk_fma_f32 v[102:103], v[196:197], v[102:103], v[112:113] neg_lo:[1,0,0] neg_hi:[1,0,0]
	v_pk_fma_f32 v[116:117], v[196:197], v[98:99], v[116:117] neg_lo:[1,0,0] neg_hi:[1,0,0]
	v_pk_mul_f32 v[94:95], v[106:107], v[106:107]
	v_pk_mul_f32 v[112:113], v[104:105], v[104:105]
	v_pk_mul_f32 v[98:99], v[102:103], v[102:103]
	v_pk_mul_f32 v[114:115], v[116:117], v[116:117]
	v_mov_b32_e32 v118, v112
	v_mov_b32_e32 v119, v94
	v_mov_b32_e32 v94, v113
	v_mov_b32_e32 v112, v114
	v_mov_b32_e32 v113, v98
	v_pk_add_f32 v[94:95], v[118:119], v[94:95]
	v_mov_b32_e32 v98, v115
	v_pk_add_f32 v[94:95], v[94:95], v[112:113]
	v_mov_b32_e32 v112, v50
	v_pk_add_f32 v[94:95], v[94:95], v[98:99]
	ds_bpermute_b32 v99, v210, v95
	ds_bpermute_b32 v98, v210, v94
	v_mov_b32_e32 v113, v66
	s_waitcnt vmcnt(8)
	v_mul_f32_e32 v111, 0x3f24fd5c, v127
	v_mov_b32_e32 v118, v19
	v_mov_b32_e32 v119, v35
	s_waitcnt lgkmcnt(0)
	v_pk_add_f32 v[98:99], v[94:95], v[98:99]
	ds_bpermute_b32 v115, v209, v99
	ds_bpermute_b32 v114, v209, v98
	v_lshl_add_u64 v[94:95], s[14:15], 0, v[86:87]
	v_pk_mul_f32 v[86:87], v[108:109], v[100:101] op_sel_hi:[1,0]
	v_pk_mul_f32 v[108:109], v[112:113], v[100:101] op_sel_hi:[1,0]
	v_mul_f32_e32 v113, 0x3f24fd5c, v125
	s_waitcnt lgkmcnt(0)
	v_pk_add_f32 v[98:99], v[98:99], v[114:115]
	ds_bpermute_b32 v123, v208, v99
	ds_bpermute_b32 v122, v208, v98
	v_mul_f32_e32 v114, 0x3f24fd5c, v124
	s_waitcnt vmcnt(7)
; __device__ __forceinline__ unsigned cvtpk_s(float lo, float hi) { f32x2_t v = {lo, hi}; bf16x2_t b = __builtin_convertvector(v, bf16x2_t); return __builtin_bit_cast(unsigned, b); }
; __device__ __forceinline__ void attn_unit(LAS unsigned char* lds, const bf16_t* Qb, const bf16_t* Kb, const bf16_t* VT, bf16_t* O1, bf16_t* OC, const float* subg, const unsigned* kmx, float lam, int b, int hm, int qb, bool first, bool has_next, int b2, int hm2) {
;     ...
;             for (int s4 = 0; s4 < 4; ++s4) { const int r = 4 * q4 + s4, q = 8 * q4 + 4 * hi + s4; float ov[4]; float ss = 0.f;
; #pragma unroll
;                 for (int db = 0; db < 4; ++db) { const float x1 = __uint_as_float((unsigned)O1[obase + (size_t)q * DM + db * 32] << 16); ov[db] = x1 - lam * (o[db][r] * fv[s4]); ss += ov[db] * ov[db]; }
;                 ss += __shfl_xor(ss, 1); ss += __shfl_xor(ss, 2); ss += __shfl_xor(ss, 4); ss += __shfl_xor(ss, 8); ss += __shfl_xor(ss, 16);
;                 const float rstd = rsqrtf(ss * (1.0f / 128.0f) + EPS);
; #pragma unroll
;                 for (int db = 0; db < 4; ++db) { const unsigned w = cvtpk_s(ov[db] * rstd * gs[db], 0.f); OC[obase + (size_t)q * DM + db * 32] = (bf16_t)(w & 0xffffu); } } }
	v_lshlrev_b32_e32 v125, 16, v128
	s_waitcnt vmcnt(2)
	v_lshlrev_b32_e32 v124, 16, v133
	v_pk_fma_f32 v[124:125], v[196:197], v[86:87], v[124:125] neg_lo:[1,0,0] neg_hi:[1,0,0]
	s_waitcnt lgkmcnt(0)
	v_pk_add_f32 v[98:99], v[98:99], v[122:123]
	ds_bpermute_b32 v123, v207, v99
	ds_bpermute_b32 v122, v207, v98
	v_mul_f32_e32 v112, 0x3f24fd5c, v126
	v_lshl_add_u64 v[120:121], v[94:95], 0, v[198:199]
	v_lshlrev_b32_e32 v126, 16, v129
	s_waitcnt vmcnt(0)
	v_lshlrev_b32_e32 v129, 16, v135
	s_waitcnt lgkmcnt(0)
	v_pk_add_f32 v[98:99], v[98:99], v[122:123]
	ds_bpermute_b32 v123, v206, v99
	ds_bpermute_b32 v122, v206, v98
	v_lshlrev_b32_e32 v128, 16, v132
	v_lshlrev_b32_e32 v127, 16, v134
	v_pk_fma_f32 v[108:109], v[196:197], v[108:109], v[126:127] neg_lo:[1,0,0] neg_hi:[1,0,0]
	v_lshl_add_u64 v[84:85], v[94:95], 0, v[84:85]
	s_waitcnt lgkmcnt(0)
	v_pk_add_f32 v[86:87], v[98:99], v[122:123]
	v_pk_mul_f32 v[126:127], v[108:109], v[108:109]
	v_pk_fma_f32 v[122:123], v[86:87], s[22:23], v[92:93] op_sel_hi:[1,0,0]
	s_nop 0
	v_mul_f32_e32 v86, 0x4b800000, v123
	v_cmp_gt_f32_e32 vcc, s37, v123
	v_mul_f32_e32 v115, 0x4b800000, v122
	s_nop 0
	v_cndmask_b32_e32 v86, v123, v86, vcc
	v_rsq_f32_e32 v98, v86
	v_pk_mul_f32 v[86:87], v[124:125], v[124:125]
	v_mul_f32_e32 v99, 0x45800000, v98
	v_cndmask_b32_e32 v98, v98, v99, vcc
	v_mul_f32_e32 v99, v106, v98
	v_mul_f32_e32 v100, v107, v98
	v_mul_f32_e32 v102, v102, v98
	v_mul_f32_e32 v98, v103, v98
	v_mul_f32_e32 v99, v114, v99
	v_mul_f32_e32 v98, v111, v98
	v_mul_f32_e32 v100, v113, v100
	v_mul_f32_e32 v102, v112, v102
	v_cvt_pk_bf16_f32 v99, v99, s0
	v_cvt_pk_bf16_f32 v98, v98, s0
	v_cvt_pk_bf16_f32 v100, v100, s0
	v_cvt_pk_bf16_f32 v102, v102, s0
	global_store_short v[120:121], v99, off
	global_store_short v[120:121], v100, off offset:64
	global_store_short v[120:121], v102, off offset:128
	global_store_short v[120:121], v98, off offset:192
	v_mov_b32_e32 v98, v101
	v_pk_mul_f32 v[100:101], v[118:119], v[98:99] op_sel_hi:[1,0]
	v_mov_b32_e32 v118, v51
	v_mov_b32_e32 v119, v67
	v_pk_fma_f32 v[102:103], v[196:197], v[100:101], v[128:129] neg_lo:[1,0,0] neg_hi:[1,0,0]
	v_lshlrev_b32_e32 v101, 16, v131
	v_lshlrev_b32_e32 v100, 16, v130
	v_pk_mul_f32 v[98:99], v[118:119], v[98:99] op_sel_hi:[1,0]
	v_pk_mul_f32 v[106:107], v[102:103], v[102:103]
	v_pk_fma_f32 v[100:101], v[196:197], v[98:99], v[100:101] neg_lo:[1,0,0] neg_hi:[1,0,0]
	v_or_b32_e32 v98, 0x4000, v198
	v_pk_mul_f32 v[118:119], v[100:101], v[100:101]
	v_mov_b32_e32 v99, v199
	v_mov_b32_e32 v130, v106
	v_mov_b32_e32 v131, v86
	v_mov_b32_e32 v86, v107
	v_lshl_add_u64 v[128:129], v[90:91], 0, v[98:99]
	v_pk_add_f32 v[86:87], v[130:131], v[86:87]
	v_mov_b32_e32 v106, v118
	v_mov_b32_e32 v107, v126
	global_load_ushort v123, v[128:129], off
	global_load_ushort v132, v[128:129], off offset:64
	global_load_ushort v130, v[128:129], off offset:128
	global_load_ushort v131, v[128:129], off offset:192
	v_pk_add_f32 v[106:107], v[86:87], v[106:107]
	v_or_b32_e32 v86, 0x4800, v198
	v_mov_b32_e32 v87, v199
	v_lshl_add_u64 v[128:129], v[90:91], 0, v[86:87]
	global_load_ushort v133, v[128:129], off
	global_load_ushort v134, v[128:129], off offset:64
	v_mov_b32_e32 v126, v119
	v_pk_add_f32 v[106:107], v[106:107], v[126:127]
	global_load_ushort v126, v[128:129], off offset:128
	global_load_ushort v127, v[128:129], off offset:192
	ds_bpermute_b32 v119, v210, v107
	ds_bpermute_b32 v118, v210, v106
	v_cmp_gt_f32_e32 vcc, s37, v122
	v_lshl_add_u64 v[86:87], v[94:95], 0, v[86:87]
	s_waitcnt lgkmcnt(0)
	v_pk_add_f32 v[106:107], v[106:107], v[118:119]
	v_cndmask_b32_e32 v115, v122, v115, vcc
	ds_bpermute_b32 v119, v209, v107
	ds_bpermute_b32 v118, v209, v106
	v_rsq_f32_e32 v115, v115
	s_waitcnt lgkmcnt(0)
	v_pk_add_f32 v[106:107], v[106:107], v[118:119]
	v_mul_f32_e32 v122, 0x45800000, v115
	v_cndmask_b32_e32 v115, v115, v122, vcc
	ds_bpermute_b32 v119, v208, v107
	ds_bpermute_b32 v118, v208, v106
	v_mul_f32_e32 v104, v104, v115
	v_mul_f32_e32 v104, v114, v104
	v_cvt_pk_bf16_f32 v104, v104, s0
	global_store_short v[120:121], v104, off offset:2048
	v_mul_f32_e32 v104, v105, v115
	v_mul_f32_e32 v122, v113, v104
	s_waitcnt lgkmcnt(0)
	v_pk_add_f32 v[104:105], v[106:107], v[118:119]
	ds_bpermute_b32 v107, v207, v105
	ds_bpermute_b32 v106, v207, v104
	v_mul_f32_e32 v116, v116, v115
	v_mul_f32_e32 v116, v112, v116
	v_cvt_pk_bf16_f32 v116, v116, s0
	global_store_short v[120:121], v116, off offset:2176
	s_waitcnt lgkmcnt(0)
	v_pk_add_f32 v[104:105], v[104:105], v[106:107]
	ds_bpermute_b32 v107, v206, v105
	ds_bpermute_b32 v106, v206, v104
	v_mul_f32_e32 v115, v117, v115
	v_lshl_add_u64 v[116:117], v[94:95], 0, v[96:97]
	v_mul_f32_e32 v115, v111, v115
	v_cvt_pk_bf16_f32 v118, v122, s0
	s_waitcnt lgkmcnt(0)
	v_pk_add_f32 v[104:105], v[104:105], v[106:107]
	global_store_short v[120:121], v118, off offset:2112
	v_pk_fma_f32 v[104:105], v[104:105], s[22:23], v[92:93] op_sel_hi:[1,0,0]
	s_waitcnt vmcnt(7)
	v_lshlrev_b32_e32 v107, 16, v131
	v_mul_f32_e32 v106, 0x4b800000, v105
	v_cmp_gt_f32_e32 vcc, s37, v105
	s_waitcnt vmcnt(4)
; #define LAS __attribute__((address_space(3)))
; __device__ __forceinline__ unsigned cvtpk_s(float lo, float hi) { f32x2_t v = {lo, hi}; bf16x2_t b = __builtin_convertvector(v, bf16x2_t); return __builtin_bit_cast(unsigned, b); }
; __device__ __forceinline__ void attn_unit(LAS unsigned char* lds, const bf16_t* Qb, const bf16_t* Kb, const bf16_t* VT, bf16_t* O1, bf16_t* OC, const float* subg, const unsigned* kmx, float lam, int b, int hm, int qb, bool first, bool has_next, int b2, int hm2) {
;     ...
;         for (int q4 = 0; q4 < 4; ++q4) { const f32x4 fv = *(const LAS f32x4*)(wsf + 8 * q4 + 4 * hi);
; #pragma unroll
;             for (int s4 = 0; s4 < 4; ++s4) { const int r = 4 * q4 + s4, q = 8 * q4 + 4 * hi + s4; float ov[4]; float ss = 0.f;
; #pragma unroll
;                 for (int db = 0; db < 4; ++db) { const float x1 = __uint_as_float((unsigned)O1[obase + (size_t)q * DM + db * 32] << 16); ov[db] = x1 - lam * (o[db][r] * fv[s4]); ss += ov[db] * ov[db]; }
;                 ss += __shfl_xor(ss, 1); ss += __shfl_xor(ss, 2); ss += __shfl_xor(ss, 4); ss += __shfl_xor(ss, 8); ss += __shfl_xor(ss, 16);
;                 const float rstd = rsqrtf(ss * (1.0f / 128.0f) + EPS);
; #pragma unroll
;                 for (int db = 0; db < 4; ++db) { const unsigned w = cvtpk_s(ov[db] * rstd * gs[db], 0.f); OC[obase + (size_t)q * DM + db * 32] = (bf16_t)(w & 0xffffu); } } }
	v_lshlrev_b32_e32 v122, 16, v126
	v_cndmask_b32_e32 v105, v105, v106, vcc
	v_rsq_f32_e32 v105, v105
	v_cvt_pk_bf16_f32 v106, v115, s0
	global_store_short v[120:121], v106, off offset:2240
	v_lshlrev_b32_e32 v106, 16, v130
	v_mul_f32_e32 v96, 0x45800000, v105
	v_cndmask_b32_e32 v96, v105, v96, vcc
	v_mul_f32_e32 v97, v124, v96
	v_mul_f32_e32 v97, v114, v97
	v_cvt_pk_bf16_f32 v97, v97, s0
	global_store_short v[116:117], v97, off
	v_mul_f32_e32 v97, v125, v96
	v_mul_f32_e32 v97, v113, v97
	v_cvt_pk_bf16_f32 v97, v97, s0
	global_store_short v[116:117], v97, off offset:64
	v_mul_f32_e32 v97, v108, v96
	v_mul_f32_e32 v115, v109, v96
	v_mov_b32_e32 v108, v52
	v_mov_b32_e32 v109, v68
	v_mul_f32_e32 v97, v112, v97
	v_mul_f32_e32 v96, 0x4b800000, v104
	v_cmp_gt_f32_e32 vcc, s37, v104
	v_pk_mul_f32 v[108:109], v[108:109], v[80:81] op_sel_hi:[1,0]
	v_cvt_pk_bf16_f32 v97, v97, s0
	v_cndmask_b32_e32 v96, v104, v96, vcc
	v_mov_b32_e32 v104, v20
	v_mov_b32_e32 v105, v36
	v_pk_fma_f32 v[118:119], v[196:197], v[108:109], v[106:107] neg_lo:[1,0,0] neg_hi:[1,0,0]
	v_mov_b32_e32 v108, v21
	v_mov_b32_e32 v109, v37
	global_store_short v[116:117], v97, off offset:128
	v_rsq_f32_e32 v128, v96
	v_lshlrev_b32_e32 v97, 16, v132
	v_lshlrev_b32_e32 v96, 16, v123
	v_pk_mul_f32 v[104:105], v[104:105], v[80:81] op_sel_hi:[1,0]
	v_lshlrev_b32_e32 v107, 16, v134
	v_lshlrev_b32_e32 v106, 16, v133
	v_pk_mul_f32 v[108:109], v[108:109], v[80:81] op_sel:[0,1]
	v_mov_b32_e32 v124, v53
	v_mov_b32_e32 v125, v69
	v_pk_fma_f32 v[104:105], v[196:197], v[104:105], v[96:97] neg_lo:[1,0,0] neg_hi:[1,0,0]
	v_pk_fma_f32 v[106:107], v[196:197], v[108:109], v[106:107] neg_lo:[1,0,0] neg_hi:[1,0,0]
	s_waitcnt vmcnt(7)
	v_lshlrev_b32_e32 v123, 16, v127
	v_pk_mul_f32 v[80:81], v[124:125], v[80:81] op_sel:[0,1]
	v_pk_mul_f32 v[96:97], v[104:105], v[104:105]
	v_pk_mul_f32 v[108:109], v[106:107], v[106:107]
	v_pk_fma_f32 v[80:81], v[196:197], v[80:81], v[122:123] neg_lo:[1,0,0] neg_hi:[1,0,0]
	v_pk_mul_f32 v[120:121], v[118:119], v[118:119]
	v_pk_mul_f32 v[122:123], v[80:81], v[80:81]
	v_mov_b32_e32 v124, v108
	v_mov_b32_e32 v125, v96
	v_mov_b32_e32 v96, v109
	v_or_b32_e32 v108, 0x5000, v198
	v_mov_b32_e32 v109, v199
	v_lshl_add_u64 v[126:127], v[90:91], 0, v[108:109]
	v_pk_add_f32 v[96:97], v[124:125], v[96:97]
	v_mov_b32_e32 v124, v122
	v_mov_b32_e32 v125, v120
	global_load_ushort v129, v[126:127], off
	global_load_ushort v130, v[126:127], off offset:64
	v_pk_add_f32 v[96:97], v[96:97], v[124:125]
	v_mov_b32_e32 v120, v123
	global_load_ushort v131, v[126:127], off offset:128
	s_nop 0
	global_load_ushort v126, v[126:127], off offset:192
	v_pk_add_f32 v[120:121], v[96:97], v[120:121]
	v_or_b32_e32 v96, 0x5800, v198
	v_mov_b32_e32 v97, v199
	v_mul_f32_e32 v115, v111, v115
	v_lshl_add_u64 v[124:125], v[90:91], 0, v[96:97]
	v_cvt_pk_bf16_f32 v115, v115, s0
	global_load_ushort v127, v[124:125], off
	global_load_ushort v132, v[124:125], off offset:64
	ds_bpermute_b32 v123, v210, v121
	global_store_short v[116:117], v115, off offset:192
	global_load_ushort v133, v[124:125], off offset:128
	s_nop 0
	global_load_ushort v124, v[124:125], off offset:192
	ds_bpermute_b32 v122, v210, v120
	v_mul_f32_e32 v115, 0x45800000, v128
	v_cndmask_b32_e32 v115, v128, v115, vcc
	v_mul_f32_e32 v102, v102, v115
	v_mul_f32_e32 v102, v114, v102
	s_waitcnt lgkmcnt(0)
	v_pk_add_f32 v[116:117], v[120:121], v[122:123]
	ds_bpermute_b32 v121, v209, v117
	ds_bpermute_b32 v120, v209, v116
	v_cvt_pk_bf16_f32 v102, v102, s0
	global_store_short v[84:85], v102, off
	v_mul_f32_e32 v102, v103, v115
	v_mul_f32_e32 v122, v113, v102
	s_waitcnt lgkmcnt(0)
	v_pk_add_f32 v[116:117], v[116:117], v[120:121]
	ds_bpermute_b32 v121, v208, v117
	ds_bpermute_b32 v120, v208, v116
	v_mul_f32_e32 v100, v100, v115
	v_mul_f32_e32 v100, v112, v100
	v_cvt_pk_bf16_f32 v100, v100, s0
	global_store_short v[84:85], v100, off offset:128
	s_waitcnt lgkmcnt(0)
	v_pk_add_f32 v[102:103], v[116:117], v[120:121]
	ds_bpermute_b32 v117, v207, v103
	ds_bpermute_b32 v116, v207, v102
	v_mul_f32_e32 v100, v101, v115
	v_mul_f32_e32 v115, v111, v100
	v_cvt_pk_bf16_f32 v120, v122, s0
	global_store_short v[84:85], v120, off offset:64
	s_waitcnt lgkmcnt(0)
	v_pk_add_f32 v[102:103], v[102:103], v[116:117]
	ds_bpermute_b32 v117, v206, v103
	ds_bpermute_b32 v116, v206, v102
	v_lshl_add_u64 v[96:97], v[94:95], 0, v[96:97]
	s_waitcnt lgkmcnt(0)
	v_pk_add_f32 v[100:101], v[102:103], v[116:117]
	s_nop 0
	v_pk_fma_f32 v[100:101], v[100:101], s[22:23], v[92:93] op_sel_hi:[1,0,0]
	v_mov_b32_e32 v103, v70
	v_mul_f32_e32 v102, 0x4b800000, v101
	v_cmp_gt_f32_e32 vcc, s37, v101
	s_nop 1
	v_cndmask_b32_e32 v101, v101, v102, vcc
	v_rsq_f32_e32 v101, v101
	v_cvt_pk_bf16_f32 v102, v115, s0
	global_store_short v[84:85], v102, off offset:192
	v_lshl_add_u64 v[84:85], v[94:95], 0, v[98:99]
	v_mul_f32_e32 v98, 0x45800000, v101
	v_cndmask_b32_e32 v98, v101, v98, vcc
	v_mul_f32_e32 v99, v104, v98
	v_mul_f32_e32 v99, v114, v99
	v_cvt_pk_bf16_f32 v99, v99, s0
	global_store_short v[84:85], v99, off
	v_mul_f32_e32 v99, v105, v98
	v_mul_f32_e32 v99, v113, v99
	v_cvt_pk_bf16_f32 v99, v99, s0
	global_store_short v[84:85], v99, off offset:64
	v_mul_f32_e32 v99, v118, v98
	v_mul_f32_e32 v98, v119, v98
	v_mul_f32_e32 v98, v111, v98
	v_mul_f32_e32 v99, v112, v99
	v_cvt_pk_bf16_f32 v115, v98, s0
	v_mul_f32_e32 v98, 0x4b800000, v100
	v_cmp_gt_f32_e32 vcc, s37, v100
	v_cvt_pk_bf16_f32 v99, v99, s0
	v_mov_b32_e32 v101, v38
	v_cndmask_b32_e32 v98, v100, v98, vcc
	v_mov_b32_e32 v100, v22
	global_store_short v[84:85], v99, off offset:128
	v_rsq_f32_e32 v128, v98
	s_waitcnt vmcnt(14)
; #define LAS __attribute__((address_space(3)))
; __device__ __forceinline__ unsigned cvtpk_s(float lo, float hi) { f32x2_t v = {lo, hi}; bf16x2_t b = __builtin_convertvector(v, bf16x2_t); return __builtin_bit_cast(unsigned, b); }
; __device__ __forceinline__ void attn_unit(LAS unsigned char* lds, const bf16_t* Qb, const bf16_t* Kb, const bf16_t* VT, bf16_t* O1, bf16_t* OC, const float* subg, const unsigned* kmx, float lam, int b, int hm, int qb, bool first, bool has_next, int b2, int hm2) {
;     ...
;         for (int q4 = 0; q4 < 4; ++q4) { const f32x4 fv = *(const LAS f32x4*)(wsf + 8 * q4 + 4 * hi);
; #pragma unroll
;             for (int s4 = 0; s4 < 4; ++s4) { const int r = 4 * q4 + s4, q = 8 * q4 + 4 * hi + s4; float ov[4]; float ss = 0.f;
; #pragma unroll
;                 for (int db = 0; db < 4; ++db) { const float x1 = __uint_as_float((unsigned)O1[obase + (size_t)q * DM + db * 32] << 16); ov[db] = x1 - lam * (o[db][r] * fv[s4]); ss += ov[db] * ov[db]; }
;                 ss += __shfl_xor(ss, 1); ss += __shfl_xor(ss, 2); ss += __shfl_xor(ss, 4); ss += __shfl_xor(ss, 8); ss += __shfl_xor(ss, 16);
;                 const float rstd = rsqrtf(ss * (1.0f / 128.0f) + EPS);
; #pragma unroll
;                 for (int db = 0; db < 4; ++db) { const unsigned w = cvtpk_s(ov[db] * rstd * gs[db], 0.f); OC[obase + (size_t)q * DM + db * 32] = (bf16_t)(w & 0xffffu); } } }
	v_lshlrev_b32_e32 v99, 16, v130
	v_lshlrev_b32_e32 v98, 16, v129
	v_pk_mul_f32 v[100:101], v[100:101], v[82:83] op_sel_hi:[1,0]
	v_mov_b32_e32 v102, v54
	v_pk_fma_f32 v[116:117], v[196:197], v[100:101], v[98:99] neg_lo:[1,0,0] neg_hi:[1,0,0]
	s_waitcnt vmcnt(12)
	v_lshlrev_b32_e32 v99, 16, v126
	v_lshlrev_b32_e32 v98, 16, v131
	v_pk_mul_f32 v[102:103], v[102:103], v[82:83] op_sel_hi:[1,0]
	v_mov_b32_e32 v82, v83
	v_pk_fma_f32 v[118:119], v[196:197], v[102:103], v[98:99] neg_lo:[1,0,0] neg_hi:[1,0,0]
	v_mov_b32_e32 v102, v23
	v_mov_b32_e32 v103, v39
	s_waitcnt vmcnt(10)
	v_lshlrev_b32_e32 v99, 16, v132
	v_lshlrev_b32_e32 v98, 16, v127
	v_pk_mul_f32 v[102:103], v[102:103], v[82:83] op_sel_hi:[1,0]
	v_mov_b32_e32 v104, v55
	v_mov_b32_e32 v105, v71
	v_pk_fma_f32 v[102:103], v[196:197], v[102:103], v[98:99] neg_lo:[1,0,0] neg_hi:[1,0,0]
	s_waitcnt vmcnt(7)
	v_lshlrev_b32_e32 v99, 16, v124
	v_lshlrev_b32_e32 v98, 16, v133
	v_pk_mul_f32 v[82:83], v[104:105], v[82:83] op_sel_hi:[1,0]
	v_pk_mul_f32 v[100:101], v[116:117], v[116:117]
	v_pk_mul_f32 v[122:123], v[102:103], v[102:103]
	v_pk_fma_f32 v[98:99], v[196:197], v[82:83], v[98:99] neg_lo:[1,0,0] neg_hi:[1,0,0]
	v_pk_mul_f32 v[120:121], v[118:119], v[118:119]
	v_pk_mul_f32 v[82:83], v[98:99], v[98:99]
	v_mov_b32_e32 v126, v122
	v_mov_b32_e32 v127, v100
	v_mov_b32_e32 v100, v123
	v_or_b32_e32 v104, 0x8000, v198
	v_mov_b32_e32 v105, v199
	v_pk_add_f32 v[100:101], v[126:127], v[100:101]
	v_mov_b32_e32 v122, v82
	v_mov_b32_e32 v123, v120
	v_lshl_add_u64 v[124:125], v[90:91], 0, v[104:105]
	v_pk_add_f32 v[122:123], v[100:101], v[122:123]
	v_or_b32_e32 v100, 0x8800, v198
	v_mov_b32_e32 v101, v199
	global_load_ushort v129, v[124:125], off
	global_load_ushort v130, v[124:125], off offset:64
	global_load_ushort v126, v[124:125], off offset:128
	s_nop 0
	global_load_ushort v124, v[124:125], off offset:192
	v_mov_b32_e32 v120, v83
	v_lshl_add_u64 v[82:83], v[90:91], 0, v[100:101]
	global_load_ushort v125, v[82:83], off
	global_load_ushort v127, v[82:83], off offset:64
	v_pk_add_f32 v[120:121], v[122:123], v[120:121]
	global_store_short v[84:85], v115, off offset:192
	global_load_ushort v131, v[82:83], off offset:128
	global_load_ushort v132, v[82:83], off offset:192
	ds_bpermute_b32 v123, v210, v121
	ds_bpermute_b32 v122, v210, v120
	v_mul_f32_e32 v115, 0x45800000, v128
	v_cndmask_b32_e32 v115, v128, v115, vcc
	v_mul_f32_e32 v106, v106, v115
	v_mul_f32_e32 v106, v114, v106
	s_waitcnt lgkmcnt(0)
	v_pk_add_f32 v[82:83], v[120:121], v[122:123]
	ds_bpermute_b32 v85, v209, v83
	ds_bpermute_b32 v84, v209, v82
	v_cvt_pk_bf16_f32 v106, v106, s0
	v_mul_f32_e32 v80, v80, v115
	global_store_short v[86:87], v106, off
	v_mul_f32_e32 v106, v107, v115
	s_waitcnt lgkmcnt(0)
	v_pk_add_f32 v[82:83], v[82:83], v[84:85]
	ds_bpermute_b32 v85, v208, v83
	ds_bpermute_b32 v84, v208, v82
	v_mul_f32_e32 v80, v112, v80
	v_mul_f32_e32 v106, v113, v106
	v_cvt_pk_bf16_f32 v80, v80, s0
	v_cvt_pk_bf16_f32 v106, v106, s0
	s_waitcnt lgkmcnt(0)
	v_pk_add_f32 v[82:83], v[82:83], v[84:85]
	ds_bpermute_b32 v85, v207, v83
	ds_bpermute_b32 v84, v207, v82
	global_store_short v[86:87], v80, off offset:128
	v_mul_f32_e32 v80, v81, v115
	global_store_short v[86:87], v106, off offset:64
	v_mul_f32_e32 v106, v111, v80
	s_waitcnt lgkmcnt(0)
	v_pk_add_f32 v[82:83], v[82:83], v[84:85]
	ds_bpermute_b32 v85, v206, v83
	ds_bpermute_b32 v84, v206, v82
	v_mov_b32_e32 v120, v56
	v_mov_b32_e32 v121, v72
	v_mov_b32_e32 v128, v57
	v_lshl_add_u64 v[104:105], v[94:95], 0, v[104:105]
	s_waitcnt lgkmcnt(0)
	v_pk_add_f32 v[80:81], v[82:83], v[84:85]
	v_lshl_add_u64 v[100:101], v[94:95], 0, v[100:101]
	v_pk_fma_f32 v[80:81], v[80:81], s[22:23], v[92:93] op_sel_hi:[1,0,0]
	s_waitcnt vmcnt(7)
	v_lshlrev_b32_e32 v122, 16, v125
	v_mul_f32_e32 v82, 0x4b800000, v81
	v_cmp_gt_f32_e32 vcc, s37, v81
	v_mov_b32_e32 v125, v41
	s_waitcnt vmcnt(6)
	v_lshlrev_b32_e32 v123, 16, v127
	v_cndmask_b32_e32 v81, v81, v82, vcc
	v_rsq_f32_e32 v81, v81
	v_cvt_pk_bf16_f32 v82, v106, s0
	global_store_short v[86:87], v82, off offset:192
	v_lshl_add_u64 v[106:107], v[94:95], 0, v[108:109]
	v_mul_f32_e32 v82, 0x45800000, v81
	v_cndmask_b32_e32 v81, v81, v82, vcc
	v_mul_f32_e32 v82, v116, v81
	v_mul_f32_e32 v82, v114, v82
	v_cvt_pk_bf16_f32 v82, v82, s0
	global_store_short v[106:107], v82, off
	v_mul_f32_e32 v82, v117, v81
	v_mul_f32_e32 v82, v113, v82
	ds_read_b128 v[84:87], v110 offset:64
	v_cvt_pk_bf16_f32 v82, v82, s0
	global_store_short v[106:107], v82, off offset:64
	v_mul_f32_e32 v82, v118, v81
	v_mul_f32_e32 v82, v112, v82
	v_mul_f32_e32 v115, v119, v81
	v_mul_f32_e32 v81, 0x4b800000, v80
	v_cmp_gt_f32_e32 vcc, s37, v80
	v_cvt_pk_bf16_f32 v82, v82, s0
	v_mov_b32_e32 v116, v24
	v_cndmask_b32_e32 v80, v80, v81, vcc
	v_mov_b32_e32 v117, v40
	v_lshlrev_b32_e32 v119, 16, v124
	v_mov_b32_e32 v124, v25
	global_store_short v[106:107], v82, off offset:128
	v_rsq_f32_e32 v133, v80
	v_lshlrev_b32_e32 v109, 16, v130
	v_lshlrev_b32_e32 v108, 16, v129
	ds_read_b128 v[80:83], v110 offset:96
	s_waitcnt lgkmcnt(1)
	v_pk_mul_f32 v[116:117], v[116:117], v[84:85] op_sel_hi:[1,0]
	v_pk_mul_f32 v[124:125], v[124:125], v[84:85] op_sel:[0,1]
	v_pk_fma_f32 v[108:109], v[196:197], v[116:117], v[108:109] neg_lo:[1,0,0] neg_hi:[1,0,0]
	v_pk_fma_f32 v[122:123], v[196:197], v[124:125], v[122:123] neg_lo:[1,0,0] neg_hi:[1,0,0]
	v_pk_mul_f32 v[116:117], v[108:109], v[108:109]
	v_pk_mul_f32 v[124:125], v[122:123], v[122:123]
	v_mov_b32_e32 v129, v73
	v_pk_mul_f32 v[120:121], v[120:121], v[84:85] op_sel_hi:[1,0]
	v_pk_mul_f32 v[84:85], v[128:129], v[84:85] op_sel:[0,1]
	v_mov_b32_e32 v128, v124
	v_mov_b32_e32 v129, v116
	v_mov_b32_e32 v116, v125
	v_or_b32_e32 v124, 0x9000, v198
	v_mov_b32_e32 v125, v199
	v_lshlrev_b32_e32 v118, 16, v126
	s_waitcnt vmcnt(7)
; #define LAS __attribute__((address_space(3)))
; __device__ __forceinline__ unsigned cvtpk_s(float lo, float hi) { f32x2_t v = {lo, hi}; bf16x2_t b = __builtin_convertvector(v, bf16x2_t); return __builtin_bit_cast(unsigned, b); }
; __device__ __forceinline__ void attn_unit(LAS unsigned char* lds, const bf16_t* Qb, const bf16_t* Kb, const bf16_t* VT, bf16_t* O1, bf16_t* OC, const float* subg, const unsigned* kmx, float lam, int b, int hm, int qb, bool first, bool has_next, int b2, int hm2) {
;     ...
;         for (int q4 = 0; q4 < 4; ++q4) { const f32x4 fv = *(const LAS f32x4*)(wsf + 8 * q4 + 4 * hi);
; #pragma unroll
;             for (int s4 = 0; s4 < 4; ++s4) { const int r = 4 * q4 + s4, q = 8 * q4 + 4 * hi + s4; float ov[4]; float ss = 0.f;
; #pragma unroll
;                 for (int db = 0; db < 4; ++db) { const float x1 = __uint_as_float((unsigned)O1[obase + (size_t)q * DM + db * 32] << 16); ov[db] = x1 - lam * (o[db][r] * fv[s4]); ss += ov[db] * ov[db]; }
;                 ss += __shfl_xor(ss, 1); ss += __shfl_xor(ss, 2); ss += __shfl_xor(ss, 4); ss += __shfl_xor(ss, 8); ss += __shfl_xor(ss, 16);
;                 const float rstd = rsqrtf(ss * (1.0f / 128.0f) + EPS);
; #pragma unroll
;                 for (int db = 0; db < 4; ++db) { const unsigned w = cvtpk_s(ov[db] * rstd * gs[db], 0.f); OC[obase + (size_t)q * DM + db * 32] = (bf16_t)(w & 0xffffu); } } }
	v_lshlrev_b32_e32 v127, 16, v132
	v_lshlrev_b32_e32 v126, 16, v131
	v_lshl_add_u64 v[130:131], v[90:91], 0, v[124:125]
	v_pk_fma_f32 v[118:119], v[196:197], v[120:121], v[118:119] neg_lo:[1,0,0] neg_hi:[1,0,0]
	v_pk_fma_f32 v[126:127], v[196:197], v[84:85], v[126:127] neg_lo:[1,0,0] neg_hi:[1,0,0]
	global_load_ushort v132, v[130:131], off
	global_load_ushort v134, v[130:131], off offset:64
	v_pk_mul_f32 v[120:121], v[118:119], v[118:119]
	v_pk_mul_f32 v[84:85], v[126:127], v[126:127]
	v_pk_add_f32 v[116:117], v[128:129], v[116:117]
	v_mov_b32_e32 v128, v84
	v_mov_b32_e32 v129, v120
	v_mov_b32_e32 v120, v85
	global_load_ushort v135, v[130:131], off offset:128
	s_nop 0
	global_load_ushort v130, v[130:131], off offset:192
	v_or_b32_e32 v84, 0x9800, v198
	v_mov_b32_e32 v85, v199
	v_pk_add_f32 v[116:117], v[116:117], v[128:129]
	v_lshl_add_u64 v[128:129], v[90:91], 0, v[84:85]
	v_mul_f32_e32 v115, v111, v115
	global_load_ushort v131, v[128:129], off
	global_load_ushort v136, v[128:129], off offset:64
	v_cvt_pk_bf16_f32 v115, v115, s0
	global_store_short v[106:107], v115, off offset:192
	global_load_ushort v137, v[128:129], off offset:128
	s_nop 0
	global_load_ushort v128, v[128:129], off offset:192
	v_pk_add_f32 v[116:117], v[116:117], v[120:121]
	ds_bpermute_b32 v121, v210, v117
	ds_bpermute_b32 v120, v210, v116
	v_mul_f32_e32 v115, 0x45800000, v133
	v_cndmask_b32_e32 v115, v133, v115, vcc
	v_mul_f32_e32 v102, v102, v115
	v_mul_f32_e32 v102, v114, v102
	s_waitcnt lgkmcnt(0)
	v_pk_add_f32 v[106:107], v[116:117], v[120:121]
	ds_bpermute_b32 v117, v209, v107
	ds_bpermute_b32 v116, v209, v106
	v_cvt_pk_bf16_f32 v102, v102, s0
	global_store_short v[96:97], v102, off
	v_mul_f32_e32 v102, v103, v115
	v_mul_f32_e32 v120, v113, v102
	s_waitcnt lgkmcnt(0)
	v_pk_add_f32 v[106:107], v[106:107], v[116:117]
	ds_bpermute_b32 v117, v208, v107
	ds_bpermute_b32 v116, v208, v106
	v_mul_f32_e32 v98, v98, v115
	v_mul_f32_e32 v98, v112, v98
	v_cvt_pk_bf16_f32 v98, v98, s0
	global_store_short v[96:97], v98, off offset:128
	s_waitcnt lgkmcnt(0)
	v_pk_add_f32 v[102:103], v[106:107], v[116:117]
	ds_bpermute_b32 v107, v207, v103
	ds_bpermute_b32 v106, v207, v102
	v_mul_f32_e32 v98, v99, v115
	v_mul_f32_e32 v115, v111, v98
	v_cvt_pk_bf16_f32 v116, v120, s0
	global_store_short v[96:97], v116, off offset:64
	s_waitcnt lgkmcnt(0)
	v_pk_add_f32 v[102:103], v[102:103], v[106:107]
	ds_bpermute_b32 v107, v206, v103
	ds_bpermute_b32 v106, v206, v102
	v_lshl_add_u64 v[84:85], v[94:95], 0, v[84:85]
	s_waitcnt lgkmcnt(0)
	v_pk_add_f32 v[98:99], v[102:103], v[106:107]
	s_nop 0
	v_pk_fma_f32 v[98:99], v[98:99], s[22:23], v[92:93] op_sel_hi:[1,0,0]
	s_nop 0
	v_mul_f32_e32 v102, 0x4b800000, v99
	v_cmp_gt_f32_e32 vcc, s37, v99
	s_nop 1
	v_cndmask_b32_e32 v99, v99, v102, vcc
	v_rsq_f32_e32 v99, v99
	v_cvt_pk_bf16_f32 v102, v115, s0
	global_store_short v[96:97], v102, off offset:192
	v_mul_f32_e32 v96, 0x45800000, v99
	v_cndmask_b32_e32 v96, v99, v96, vcc
	v_mul_f32_e32 v97, v108, v96
	v_mul_f32_e32 v97, v114, v97
	v_cvt_pk_bf16_f32 v97, v97, s0
	global_store_short v[104:105], v97, off
	v_mul_f32_e32 v97, v109, v96
	v_mul_f32_e32 v97, v113, v97
	v_cvt_pk_bf16_f32 v97, v97, s0
	global_store_short v[104:105], v97, off offset:64
	v_mul_f32_e32 v97, v118, v96
	v_mul_f32_e32 v96, v119, v96
	v_mul_f32_e32 v96, v111, v96
	v_mul_f32_e32 v97, v112, v97
	v_cvt_pk_bf16_f32 v115, v96, s0
	v_mul_f32_e32 v96, 0x4b800000, v98
	v_cmp_gt_f32_e32 vcc, s37, v98
	v_cvt_pk_bf16_f32 v97, v97, s0
	v_mov_b32_e32 v99, v42
	v_cndmask_b32_e32 v96, v98, v96, vcc
	v_mov_b32_e32 v98, v26
	global_store_short v[104:105], v97, off offset:128
	v_rsq_f32_e32 v133, v96
	s_waitcnt vmcnt(14)
	v_lshlrev_b32_e32 v97, 16, v134
	v_lshlrev_b32_e32 v96, 16, v132
	v_pk_mul_f32 v[98:99], v[98:99], v[86:87] op_sel_hi:[1,0]
	s_nop 0
	v_pk_fma_f32 v[106:107], v[196:197], v[98:99], v[96:97] neg_lo:[1,0,0] neg_hi:[1,0,0]
	v_mov_b32_e32 v98, v58
	v_mov_b32_e32 v99, v74
	s_waitcnt vmcnt(12)
	v_lshlrev_b32_e32 v97, 16, v130
	v_lshlrev_b32_e32 v96, 16, v135
	v_pk_mul_f32 v[98:99], v[98:99], v[86:87] op_sel_hi:[1,0]
	v_mov_b32_e32 v86, v87
	v_pk_fma_f32 v[116:117], v[196:197], v[98:99], v[96:97] neg_lo:[1,0,0] neg_hi:[1,0,0]
	v_mov_b32_e32 v98, v27
	v_mov_b32_e32 v99, v43
	s_waitcnt vmcnt(10)
	v_lshlrev_b32_e32 v97, 16, v136
	v_lshlrev_b32_e32 v96, 16, v131
	v_pk_mul_f32 v[98:99], v[98:99], v[86:87] op_sel_hi:[1,0]
	v_pk_mul_f32 v[108:109], v[106:107], v[106:107]
	v_pk_fma_f32 v[102:103], v[196:197], v[98:99], v[96:97] neg_lo:[1,0,0] neg_hi:[1,0,0]
	v_mov_b32_e32 v98, v59
	v_mov_b32_e32 v99, v75
	s_waitcnt vmcnt(7)
	v_lshlrev_b32_e32 v97, 16, v128
	v_lshlrev_b32_e32 v96, 16, v137
	v_pk_mul_f32 v[86:87], v[98:99], v[86:87] op_sel_hi:[1,0]
	v_pk_mul_f32 v[120:121], v[102:103], v[102:103]
	v_pk_fma_f32 v[98:99], v[196:197], v[86:87], v[96:97] neg_lo:[1,0,0] neg_hi:[1,0,0]
	v_or_b32_e32 v96, 0xc000, v198
	v_mov_b32_e32 v97, v199
	v_pk_mul_f32 v[118:119], v[116:117], v[116:117]
	v_pk_mul_f32 v[86:87], v[98:99], v[98:99]
	v_mov_b32_e32 v128, v120
	v_lshl_add_u64 v[130:131], v[90:91], 0, v[96:97]
	v_mov_b32_e32 v129, v108
	v_mov_b32_e32 v108, v121
	global_load_ushort v132, v[130:131], off
	global_load_ushort v134, v[130:131], off offset:64
	v_pk_add_f32 v[108:109], v[128:129], v[108:109]
	v_mov_b32_e32 v120, v86
	v_mov_b32_e32 v121, v118
	v_mov_b32_e32 v118, v87
	v_or_b32_e32 v86, 0xc800, v198
	v_mov_b32_e32 v87, v199
	global_load_ushort v128, v[130:131], off offset:128
	global_load_ushort v129, v[130:131], off offset:192
	v_pk_add_f32 v[108:109], v[108:109], v[120:121]
	v_lshl_add_u64 v[120:121], v[90:91], 0, v[86:87]
	global_load_ushort v130, v[120:121], off
	global_load_ushort v131, v[120:121], off offset:64
	v_pk_add_f32 v[108:109], v[108:109], v[118:119]
	global_store_short v[104:105], v115, off offset:192
	global_load_ushort v135, v[120:121], off offset:128
	global_load_ushort v136, v[120:121], off offset:192
	ds_bpermute_b32 v119, v210, v109
	ds_bpermute_b32 v118, v210, v108
	v_mul_f32_e32 v115, 0x45800000, v133
	v_cndmask_b32_e32 v115, v133, v115, vcc
	v_mov_b32_e32 v120, v29
	v_mov_b32_e32 v121, v45
	s_waitcnt lgkmcnt(0)
; #define LAS __attribute__((address_space(3)))
; __device__ __forceinline__ unsigned cvtpk_s(float lo, float hi) { f32x2_t v = {lo, hi}; bf16x2_t b = __builtin_convertvector(v, bf16x2_t); return __builtin_bit_cast(unsigned, b); }
; __device__ __forceinline__ void attn_unit(LAS unsigned char* lds, const bf16_t* Qb, const bf16_t* Kb, const bf16_t* VT, bf16_t* O1, bf16_t* OC, const float* subg, const unsigned* kmx, float lam, int b, int hm, int qb, bool first, bool has_next, int b2, int hm2) {
;     ...
;         for (int q4 = 0; q4 < 4; ++q4) { const f32x4 fv = *(const LAS f32x4*)(wsf + 8 * q4 + 4 * hi);
; #pragma unroll
;             for (int s4 = 0; s4 < 4; ++s4) { const int r = 4 * q4 + s4, q = 8 * q4 + 4 * hi + s4; float ov[4]; float ss = 0.f;
; #pragma unroll
;                 for (int db = 0; db < 4; ++db) { const float x1 = __uint_as_float((unsigned)O1[obase + (size_t)q * DM + db * 32] << 16); ov[db] = x1 - lam * (o[db][r] * fv[s4]); ss += ov[db] * ov[db]; }
;                 ss += __shfl_xor(ss, 1); ss += __shfl_xor(ss, 2); ss += __shfl_xor(ss, 4); ss += __shfl_xor(ss, 8); ss += __shfl_xor(ss, 16);
;                 const float rstd = rsqrtf(ss * (1.0f / 128.0f) + EPS);
; #pragma unroll
;                 for (int db = 0; db < 4; ++db) { const unsigned w = cvtpk_s(ov[db] * rstd * gs[db], 0.f); OC[obase + (size_t)q * DM + db * 32] = (bf16_t)(w & 0xffffu); } } }
	v_pk_add_f32 v[104:105], v[108:109], v[118:119]
	ds_bpermute_b32 v109, v209, v105
	ds_bpermute_b32 v108, v209, v104
	v_mul_f32_e32 v118, v122, v115
	v_mul_f32_e32 v118, v114, v118
	v_cvt_pk_bf16_f32 v118, v118, s0
	global_store_short v[100:101], v118, off
	s_waitcnt lgkmcnt(0)
	v_pk_add_f32 v[104:105], v[104:105], v[108:109]
	ds_bpermute_b32 v109, v208, v105
	ds_bpermute_b32 v108, v208, v104
	v_mul_f32_e32 v118, v123, v115
	v_mul_f32_e32 v118, v113, v118
	v_cvt_pk_bf16_f32 v118, v118, s0
	global_store_short v[100:101], v118, off offset:64
	s_waitcnt lgkmcnt(0)
	v_pk_add_f32 v[104:105], v[104:105], v[108:109]
	ds_bpermute_b32 v109, v207, v105
	ds_bpermute_b32 v108, v207, v104
	v_mul_f32_e32 v118, v126, v115
	v_mul_f32_e32 v115, v127, v115
	v_mul_f32_e32 v118, v112, v118
	v_mul_f32_e32 v115, v111, v115
	s_waitcnt lgkmcnt(0)
	v_pk_add_f32 v[104:105], v[104:105], v[108:109]
	ds_bpermute_b32 v109, v206, v105
	ds_bpermute_b32 v108, v206, v104
	v_cvt_pk_bf16_f32 v118, v118, s0
	global_store_short v[100:101], v118, off offset:128
	v_pk_mul_f32 v[120:121], v[120:121], v[80:81] op_sel:[0,1]
	v_lshl_add_u64 v[86:87], v[94:95], 0, v[86:87]
	s_waitcnt lgkmcnt(0)
	v_pk_add_f32 v[104:105], v[104:105], v[108:109]
	s_waitcnt vmcnt(4)
	v_lshlrev_b32_e32 v122, 16, v135
	v_pk_fma_f32 v[104:105], v[104:105], s[22:23], v[92:93] op_sel_hi:[1,0,0]
	s_waitcnt vmcnt(3)
	v_lshlrev_b32_e32 v123, 16, v136
	v_mul_f32_e32 v108, 0x4b800000, v105
	v_cmp_gt_f32_e32 vcc, s37, v105
	s_nop 1
	v_cndmask_b32_e32 v105, v105, v108, vcc
	v_rsq_f32_e32 v105, v105
	v_cvt_pk_bf16_f32 v108, v115, s0
	global_store_short v[100:101], v108, off offset:192
	v_lshl_add_u64 v[108:109], v[94:95], 0, v[124:125]
	v_mul_f32_e32 v100, 0x45800000, v105
	v_cndmask_b32_e32 v100, v105, v100, vcc
	v_mul_f32_e32 v101, v106, v100
	v_mul_f32_e32 v101, v114, v101
	v_cvt_pk_bf16_f32 v101, v101, s0
	global_store_short v[108:109], v101, off
	v_mul_f32_e32 v101, v107, v100
	v_mul_f32_e32 v101, v113, v101
	v_cvt_pk_bf16_f32 v101, v101, s0
	global_store_short v[108:109], v101, off offset:64
	v_mul_f32_e32 v101, v116, v100
	v_mul_f32_e32 v100, v117, v100
	v_mul_f32_e32 v100, v111, v100
	v_mul_f32_e32 v101, v112, v101
	v_cvt_pk_bf16_f32 v115, v100, s0
	v_mul_f32_e32 v100, 0x4b800000, v104
	v_cmp_gt_f32_e32 vcc, s37, v104
	v_cvt_pk_bf16_f32 v101, v101, s0
	v_mov_b32_e32 v105, v44
	v_cndmask_b32_e32 v100, v104, v100, vcc
	v_mov_b32_e32 v104, v28
	global_store_short v[108:109], v101, off offset:128
	v_rsq_f32_e32 v133, v100
	v_lshlrev_b32_e32 v101, 16, v134
	v_lshlrev_b32_e32 v100, 16, v132
	v_pk_mul_f32 v[104:105], v[104:105], v[80:81] op_sel_hi:[1,0]
	v_mov_b32_e32 v116, v60
	v_mov_b32_e32 v117, v76
	v_pk_fma_f32 v[104:105], v[196:197], v[104:105], v[100:101] neg_lo:[1,0,0] neg_hi:[1,0,0]
	v_lshlrev_b32_e32 v101, 16, v129
	v_lshlrev_b32_e32 v100, 16, v128
	v_pk_mul_f32 v[116:117], v[116:117], v[80:81] op_sel_hi:[1,0]
	v_mov_b32_e32 v124, v61
	v_pk_fma_f32 v[116:117], v[196:197], v[116:117], v[100:101] neg_lo:[1,0,0] neg_hi:[1,0,0]
	v_lshlrev_b32_e32 v101, 16, v131
	v_lshlrev_b32_e32 v100, 16, v130
	v_mov_b32_e32 v125, v77
	v_pk_fma_f32 v[100:101], v[196:197], v[120:121], v[100:101] neg_lo:[1,0,0] neg_hi:[1,0,0]
	v_pk_mul_f32 v[80:81], v[124:125], v[80:81] op_sel:[0,1]
	v_pk_mul_f32 v[106:107], v[104:105], v[104:105]
	v_pk_mul_f32 v[120:121], v[100:101], v[100:101]
	v_pk_fma_f32 v[80:81], v[196:197], v[80:81], v[122:123] neg_lo:[1,0,0] neg_hi:[1,0,0]
	v_or_b32_e32 v122, 0xd000, v198
	v_mov_b32_e32 v123, v199
	v_lshl_add_u64 v[124:125], v[90:91], 0, v[122:123]
	v_mov_b32_e32 v128, v120
	v_mov_b32_e32 v129, v106
	v_mov_b32_e32 v106, v121
	global_load_ushort v130, v[124:125], off
	global_load_ushort v131, v[124:125], off offset:64
	v_pk_add_f32 v[106:107], v[128:129], v[106:107]
	global_load_ushort v128, v[124:125], off offset:128
	global_load_ushort v129, v[124:125], off offset:192
	v_or_b32_e32 v124, 0xd800, v198
	v_mov_b32_e32 v125, v199
	v_pk_mul_f32 v[126:127], v[80:81], v[80:81]
	v_lshl_add_u64 v[90:91], v[90:91], 0, v[124:125]
	v_mov_b32_e32 v120, v126
	global_load_ushort v126, v[90:91], off
	global_load_ushort v132, v[90:91], off offset:64
	v_pk_mul_f32 v[118:119], v[116:117], v[116:117]
	global_store_short v[108:109], v115, off offset:192
	global_load_ushort v108, v[90:91], off offset:128
	s_nop 0
	global_load_ushort v109, v[90:91], off offset:192
	v_mov_b32_e32 v121, v118
	v_pk_add_f32 v[106:107], v[106:107], v[120:121]
	v_mov_b32_e32 v118, v127
	v_pk_add_f32 v[106:107], v[106:107], v[118:119]
	ds_bpermute_b32 v119, v210, v107
	ds_bpermute_b32 v118, v210, v106
	v_mul_f32_e32 v115, 0x45800000, v133
	v_cndmask_b32_e32 v115, v133, v115, vcc
	v_mul_f32_e32 v102, v102, v115
	v_mul_f32_e32 v102, v114, v102
	s_waitcnt lgkmcnt(0)
	v_pk_add_f32 v[90:91], v[106:107], v[118:119]
	ds_bpermute_b32 v107, v209, v91
	ds_bpermute_b32 v106, v209, v90
	v_cvt_pk_bf16_f32 v102, v102, s0
	global_store_short v[84:85], v102, off
	v_mul_f32_e32 v102, v103, v115
	v_mul_f32_e32 v118, v113, v102
	s_waitcnt lgkmcnt(0)
	v_pk_add_f32 v[90:91], v[90:91], v[106:107]
	ds_bpermute_b32 v107, v208, v91
	ds_bpermute_b32 v106, v208, v90
	v_mul_f32_e32 v98, v98, v115
	v_mul_f32_e32 v98, v112, v98
	v_cvt_pk_bf16_f32 v98, v98, s0
	global_store_short v[84:85], v98, off offset:128
	s_waitcnt lgkmcnt(0)
	v_pk_add_f32 v[90:91], v[90:91], v[106:107]
	ds_bpermute_b32 v103, v207, v91
	ds_bpermute_b32 v102, v207, v90
	v_mul_f32_e32 v98, v99, v115
	v_mul_f32_e32 v98, v111, v98
	v_cvt_pk_bf16_f32 v106, v118, s0
	v_cvt_pk_bf16_f32 v98, v98, s0
	s_waitcnt lgkmcnt(0)
; #define LAS __attribute__((address_space(3)))
; __device__ __forceinline__ unsigned cvtpk_s(float lo, float hi) { f32x2_t v = {lo, hi}; bf16x2_t b = __builtin_convertvector(v, bf16x2_t); return __builtin_bit_cast(unsigned, b); }
; __device__ __forceinline__ void attn_unit(LAS unsigned char* lds, const bf16_t* Qb, const bf16_t* Kb, const bf16_t* VT, bf16_t* O1, bf16_t* OC, const float* subg, const unsigned* kmx, float lam, int b, int hm, int qb, bool first, bool has_next, int b2, int hm2) {
;     ...
;         for (int q4 = 0; q4 < 4; ++q4) { const f32x4 fv = *(const LAS f32x4*)(wsf + 8 * q4 + 4 * hi);
; #pragma unroll
;             for (int s4 = 0; s4 < 4; ++s4) { const int r = 4 * q4 + s4, q = 8 * q4 + 4 * hi + s4; float ov[4]; float ss = 0.f;
; #pragma unroll
;                 for (int db = 0; db < 4; ++db) { const float x1 = __uint_as_float((unsigned)O1[obase + (size_t)q * DM + db * 32] << 16); ov[db] = x1 - lam * (o[db][r] * fv[s4]); ss += ov[db] * ov[db]; }
;                 ss += __shfl_xor(ss, 1); ss += __shfl_xor(ss, 2); ss += __shfl_xor(ss, 4); ss += __shfl_xor(ss, 8); ss += __shfl_xor(ss, 16);
;                 const float rstd = rsqrtf(ss * (1.0f / 128.0f) + EPS);
; #pragma unroll
;                 for (int db = 0; db < 4; ++db) { const unsigned w = cvtpk_s(ov[db] * rstd * gs[db], 0.f); OC[obase + (size_t)q * DM + db * 32] = (bf16_t)(w & 0xffffu); } } }
	v_pk_add_f32 v[90:91], v[90:91], v[102:103]
	ds_bpermute_b32 v103, v206, v91
	ds_bpermute_b32 v102, v206, v90
	global_store_short v[84:85], v106, off offset:64
	global_store_short v[84:85], v98, off offset:192
	v_lshl_add_u64 v[84:85], v[94:95], 0, v[96:97]
	v_mov_b32_e32 v97, v46
	s_waitcnt lgkmcnt(0)
	v_pk_add_f32 v[90:91], v[90:91], v[102:103]
	v_mov_b32_e32 v102, v62
	v_pk_fma_f32 v[90:91], v[90:91], s[22:23], v[92:93] op_sel_hi:[1,0,0]
	v_mov_b32_e32 v103, v78
	v_mul_f32_e32 v99, 0x4b800000, v91
	v_cmp_gt_f32_e32 vcc, s37, v91
	v_pk_mul_f32 v[102:103], v[102:103], v[82:83] op_sel_hi:[1,0]
	v_mov_b32_e32 v106, v31
	v_cndmask_b32_e32 v91, v91, v99, vcc
	v_rsq_f32_e32 v91, v91
	v_mov_b32_e32 v107, v47
	v_mul_f32_e32 v96, 0x45800000, v91
	v_cndmask_b32_e32 v91, v91, v96, vcc
	v_mul_f32_e32 v96, v104, v91
	v_mul_f32_e32 v96, v114, v96
	v_cvt_pk_bf16_f32 v96, v96, s0
	global_store_short v[84:85], v96, off
	v_mul_f32_e32 v96, v105, v91
	v_mul_f32_e32 v96, v113, v96
	v_cvt_pk_bf16_f32 v96, v96, s0
	global_store_short v[84:85], v96, off offset:64
	v_mul_f32_e32 v96, v116, v91
	v_mul_f32_e32 v96, v112, v96
	v_cvt_pk_bf16_f32 v96, v96, s0
	global_store_short v[84:85], v96, off offset:128
	v_mul_f32_e32 v115, v117, v91
	v_mul_f32_e32 v91, 0x4b800000, v90
	v_cmp_gt_f32_e32 vcc, s37, v90
	v_mov_b32_e32 v96, v30
	v_pk_mul_f32 v[96:97], v[96:97], v[82:83] op_sel_hi:[1,0]
	v_cndmask_b32_e32 v90, v90, v91, vcc
	v_mov_b32_e32 v82, v83
	v_rsq_f32_e32 v118, v90
	s_waitcnt vmcnt(14)
	v_lshlrev_b32_e32 v91, 16, v131
	v_lshlrev_b32_e32 v90, 16, v130
	s_waitcnt vmcnt(11)
	v_lshlrev_b32_e32 v104, 16, v126
	s_waitcnt vmcnt(10)
	v_lshlrev_b32_e32 v105, 16, v132
	v_pk_mul_f32 v[106:107], v[106:107], v[82:83] op_sel_hi:[1,0]
	v_mov_b32_e32 v116, v63
	v_mov_b32_e32 v117, v79
	v_pk_fma_f32 v[90:91], v[196:197], v[96:97], v[90:91] neg_lo:[1,0,0] neg_hi:[1,0,0]
	v_lshlrev_b32_e32 v99, 16, v129
	v_lshlrev_b32_e32 v98, 16, v128
	v_pk_fma_f32 v[104:105], v[196:197], v[106:107], v[104:105] neg_lo:[1,0,0] neg_hi:[1,0,0]
	s_waitcnt vmcnt(7)
	v_lshlrev_b32_e32 v109, 16, v109
	v_lshlrev_b32_e32 v108, 16, v108
	v_pk_mul_f32 v[82:83], v[116:117], v[82:83] op_sel_hi:[1,0]
	v_pk_mul_f32 v[96:97], v[90:91], v[90:91]
	v_pk_fma_f32 v[98:99], v[196:197], v[102:103], v[98:99] neg_lo:[1,0,0] neg_hi:[1,0,0]
	v_pk_mul_f32 v[106:107], v[104:105], v[104:105]
	v_pk_fma_f32 v[82:83], v[196:197], v[82:83], v[108:109] neg_lo:[1,0,0] neg_hi:[1,0,0]
	v_pk_mul_f32 v[102:103], v[98:99], v[98:99]
	v_pk_mul_f32 v[108:109], v[82:83], v[82:83]
	v_mov_b32_e32 v116, v106
	v_mov_b32_e32 v117, v96
	v_mov_b32_e32 v96, v107
	v_pk_add_f32 v[96:97], v[116:117], v[96:97]
	v_mov_b32_e32 v106, v108
	v_mov_b32_e32 v107, v102
	v_pk_add_f32 v[96:97], v[96:97], v[106:107]
	v_mov_b32_e32 v102, v109
	v_pk_add_f32 v[96:97], v[96:97], v[102:103]
	ds_bpermute_b32 v103, v210, v97
	ds_bpermute_b32 v102, v210, v96
	v_mul_f32_e32 v106, v111, v115
	v_cvt_pk_bf16_f32 v106, v106, s0
	global_store_short v[84:85], v106, off offset:192
	v_mul_f32_e32 v106, 0x45800000, v118
	s_waitcnt lgkmcnt(0)
	v_pk_add_f32 v[84:85], v[96:97], v[102:103]
	ds_bpermute_b32 v97, v209, v85
	ds_bpermute_b32 v96, v209, v84
	v_cndmask_b32_e32 v102, v118, v106, vcc
	v_mul_f32_e32 v100, v100, v102
	v_mul_f32_e32 v100, v114, v100
	v_cvt_pk_bf16_f32 v100, v100, s0
	s_waitcnt lgkmcnt(0)
	v_pk_add_f32 v[84:85], v[84:85], v[96:97]
	ds_bpermute_b32 v97, v208, v85
	ds_bpermute_b32 v96, v208, v84
	v_mul_f32_e32 v80, v80, v102
	global_store_short v[86:87], v100, off
	v_mul_f32_e32 v100, v101, v102
	v_mul_f32_e32 v80, v112, v80
	s_waitcnt lgkmcnt(0)
	v_pk_add_f32 v[84:85], v[84:85], v[96:97]
	ds_bpermute_b32 v97, v207, v85
	ds_bpermute_b32 v96, v207, v84
	v_mul_f32_e32 v100, v113, v100
	v_cvt_pk_bf16_f32 v80, v80, s0
	v_cvt_pk_bf16_f32 v100, v100, s0
	global_store_short v[86:87], v80, off offset:128
	s_waitcnt lgkmcnt(0)
	v_pk_add_f32 v[84:85], v[84:85], v[96:97]
	ds_bpermute_b32 v97, v206, v85
	ds_bpermute_b32 v96, v206, v84
	v_mul_f32_e32 v80, v81, v102
	global_store_short v[86:87], v100, off offset:64
	v_mul_f32_e32 v100, v111, v80
	s_waitcnt lgkmcnt(0)
	v_pk_add_f32 v[80:81], v[84:85], v[96:97]
	s_nop 0
	v_pk_fma_f32 v[80:81], v[80:81], s[22:23], v[92:93] op_sel_hi:[1,0,0]
	s_nop 0
	v_mul_f32_e32 v84, 0x4b800000, v81
	v_cmp_gt_f32_e32 vcc, s37, v81
	s_nop 1
	v_cndmask_b32_e32 v81, v81, v84, vcc
	v_rsq_f32_e32 v81, v81
	v_cvt_pk_bf16_f32 v84, v100, s0
	global_store_short v[86:87], v84, off offset:192
	v_lshl_add_u64 v[84:85], v[94:95], 0, v[122:123]
	v_mul_f32_e32 v86, 0x45800000, v81
	v_cndmask_b32_e32 v81, v81, v86, vcc
	v_mul_f32_e32 v86, v90, v81
	v_mul_f32_e32 v86, v114, v86
	v_cvt_pk_bf16_f32 v86, v86, s0
	global_store_short v[84:85], v86, off
	v_mul_f32_e32 v86, v91, v81
	v_mul_f32_e32 v86, v113, v86
	v_cvt_pk_bf16_f32 v86, v86, s0
	global_store_short v[84:85], v86, off offset:64
	v_mul_f32_e32 v86, v98, v81
	v_mul_f32_e32 v86, v112, v86
	v_cvt_pk_bf16_f32 v86, v86, s0
	global_store_short v[84:85], v86, off offset:128
	v_mul_f32_e32 v86, 0x4b800000, v80
	v_cmp_gt_f32_e32 vcc, s37, v80
	v_mul_f32_e32 v81, v99, v81
	v_mul_f32_e32 v81, v111, v81
	v_cndmask_b32_e32 v80, v80, v86, vcc
	v_rsq_f32_e32 v80, v80
	v_cvt_pk_bf16_f32 v81, v81, s0
	global_store_short v[84:85], v81, off offset:192
	v_mul_f32_e32 v81, 0x45800000, v80
	v_cndmask_b32_e32 v84, v80, v81, vcc
	v_mul_f32_e32 v85, v104, v84
	v_mul_f32_e32 v82, v82, v84
	v_mul_f32_e32 v85, v114, v85
	v_mul_f32_e32 v82, v112, v82
	v_lshl_add_u64 v[80:81], v[94:95], 0, v[124:125]
	v_cvt_pk_bf16_f32 v85, v85, s0
	v_cvt_pk_bf16_f32 v82, v82, s0
	global_store_short v[80:81], v85, off
	v_mul_f32_e32 v85, v105, v84
	global_store_short v[80:81], v82, off offset:128
	v_mul_f32_e32 v82, v83, v84
	v_mul_f32_e32 v85, v113, v85
	v_mul_f32_e32 v82, v111, v82
	v_cvt_pk_bf16_f32 v85, v85, s0
	v_cvt_pk_bf16_f32 v82, v82, s0
	global_store_short v[80:81], v85, off offset:64
	global_store_short v[80:81], v82, off offset:192
